# DSA pair loop: bias-row fragment hoisted out of the loop, mask fragment dwords in 4 VALU instead of 6
# speedup vs baseline: 1.0085x; 1.0008x over previous
; DI void fs_reset(FState& st) { st.o0 = f16zero(); st.o1 = f16zero(); st.m = NINF; st.l = 0.f; }
; DI void dsa_task(LAS unsigned char* lds, const bf16_t* Z, const unsigned* dmask, bf16_t* YB, int b, int qi, int tid, int wave, int lane) {
;     const int r32 = lane & 31, h = lane >> 5;
;     const int tok = 32 * qi + 4 * wave + (r32 >> 3), head = r32 & 7;
;     const size_t grow = (size_t)b * SEQ + tok;
;     const bf16_t* zr = Z + grow * NZ;
;     bf16x8 qf[4];
; #pragma unroll
;     for (int s = 0; s < 4; ++s) qf[s] = *(const bf16x8*)(zr + ZC_QB + head * 64 + 16 * s + 8 * h);
;     const unsigned* dmw = dmask + ((size_t)b * SEQ + 32 * qi + 4 * wave) * 64;
;     FState st, sb; fs_reset(st); fs_reset(sb);
;     const int ntot = (qi >> 1) + 1, npair = (ntot + 1) >> 1;
;     const int skey = tid >> 3, sch = tid & 7;
;     const bf16_t* srow = Z + ((size_t)b * SEQ + skey) * NZ;
;     const int kch = (sch ^ ((skey >> 1) & 7)) * 8, vch = (sch ^ (((skey >> 1) & 1) << 2)) * 8;
;     const int wbase = wave * 1024;
;     ...
;     u32x4 wq0 = *(const u32x4*)(dmw), wq1 = *(const u32x4*)(dmw + 64), wq2 = *(const u32x4*)(dmw + 128), wq3 = *(const u32x4*)(dmw + 192);
;     DSA_DMA(0);
; __global__ void __launch_bounds__(NTHR, 2) fwd_kernel(Args a) {
;     ...
;     for (int r = 0; r * G < 2048; ++r) {
;         const int idx = r * G + ((r & 1) ? G - 1 - (int)blockIdx.x : (int)blockIdx.x);
;         if (idx >= 2048) continue;
;         const unsigned e = TASKTAB[idx]; const int k = (int)(e & 255u), bb = (int)(e >> 8);
;         int tid_ = threadIdx.x; asm volatile("" : "+v"(tid_));
;         const int lane_ = tid_ & 63;
;         if (k < 32) { if (EN_WIN || EN_SLC || EN_CMP) nsa_task(lds, Z, SELM, OCMP, YA, bb >> 1, bb & 1, k, tid_, wave, lane_); }
;         else { if (EN_DSA) dsa_task(lds, Z, DMASK, YB, bb, k - 32, tid_, wave, lane_); }
.LBB0_715:
	s_bitcmp0_b32 s67, 0
	s_cselect_b32 s5, s2, s20
	s_add_i32 s4, s5, s4
	s_cmpk_gt_i32 s4, 0x7ff
	s_cbranch_scc1 .LBB0_714
	s_ashr_i32 s5, s4, 31
	s_lshl_b64 s[4:5], s[4:5], 2
	s_add_u32 s4, s42, s4
	s_addc_u32 s5, s43, s5
	global_load_dword v2, v3, s[4:5]
	v_mov_b32_e32 v213, v0
	s_mov_b64 s[4:5], -1
	v_and_b32_e32 v214, 63, v213
	v_and_b32_e32 v215, 31, v213
	v_ashrrev_i32_e32 v194, 3, v213
	v_ashrrev_i32_e32 v206, 4, v213
	v_lshrrev_b32_e32 v4, 1, v213
	v_bfe_u32 v5, v213, 1, 3
	v_lshrrev_b32_e32 v6, 3, v213
	v_bfe_u32 v7, v213, 2, 2
	v_lshrrev_b32_e32 v210, 5, v214
	v_lshlrev_b32_e32 v8, 3, v214
	v_lshlrev_b32_e32 v9, 1, v214
	v_and_b32_e32 v169, 7, v213
	v_ashrrev_i32_e32 v195, 31, v194
	v_xor_b32_e32 v205, v206, v213
	v_lshlrev_b32_e32 v201, 7, v215
	v_and_or_b32 v211, v6, 4, v7
	v_lshlrev_b32_e32 v164, 4, v210
	v_bitop3_b32 v207, v4, v210, 7 bitop3:0x6c
	v_bitop3_b32 v208, v210, v5, 2 bitop3:0x36
	v_bitop3_b32 v209, v210, v5, 4 bitop3:0x36
	v_bitop3_b32 v212, v210, v5, 6 bitop3:0x36
	v_and_b32_e32 v202, 64, v8
	v_and_b32_e32 v203, 32, v9
	v_and_b32_e32 v204, 24, v8
	s_waitcnt vmcnt(0)
	v_readfirstlane_b32 s70, v2
	s_and_b32 s69, s70, 0xff
	s_cmp_gt_u32 s69, 31
	s_cbranch_scc0 .LBB0_736
	s_sub_i32 s10, s69, 32
	s_lshl_b32 s8, s10, 5
	s_lshr_b32 s16, s70, 8
	s_add_i32 s4, s8, s47
	v_bfe_u32 v2, v213, 3, 2
	v_or_b32_e32 v2, s4, v2
	s_lshl_b64 s[4:5], s[16:17], 11
	v_lshl_add_u64 v[166:167], s[4:5], 0, v[2:3]
	v_mov_b64_e32 v[4:5], s[22:23]
	v_mad_u64_u32 v[6:7], s[6:7], v166, s58, v[4:5]
	v_lshlrev_b32_e32 v2, 6, v214
	v_and_b32_e32 v168, 0x1c0, v2
	s_add_u32 s6, s4, s47
	v_mad_u32_u24 v7, v167, s58, v7
	v_lshlrev_b32_e32 v2, 1, v168
	s_addc_u32 s7, s5, 0
	v_lshl_add_u64 v[6:7], v[6:7], 0, v[2:3]
	v_mov_b32_e32 v165, v3
	s_add_u32 s6, s6, s8
	v_lshl_add_u64 v[6:7], v[6:7], 0, v[164:165]
	s_addc_u32 s7, s7, 0
	global_load_dwordx4 v[132:135], v[6:7], off offset:1792
	global_load_dwordx4 v[136:139], v[6:7], off offset:1824
	global_load_dwordx4 v[140:143], v[6:7], off offset:1856
	global_load_dwordx4 v[144:147], v[6:7], off offset:1888
	s_lshl_b64 s[6:7], s[6:7], 8
	v_lshl_add_u64 v[6:7], s[4:5], 0, v[194:195]
	v_lshlrev_b32_e32 v2, 3, v205
	s_add_u32 s8, s21, s6
	v_mad_u64_u32 v[170:171], s[4:5], v6, s58, v[4:5]
	v_and_b32_e32 v20, 56, v2
	v_lshlrev_b32_e32 v2, 2, v206
	s_addc_u32 s9, s68, s7
	s_lshr_b32 s71, s10, 1
	v_mad_i32_i24 v171, v7, s58, v171
	v_bitop3_b32 v10, v2, v169, 4 bitop3:0x6c
	v_lshlrev_b32_e32 v2, 1, v20
	s_add_i32 s11, s71, 2
	v_lshl_add_u64 v[6:7], v[170:171], 0, v[2:3]
	s_mov_b32 m0, s54
	s_lshr_b32 s72, s11, 1
	v_lshl_add_u64 v[6:7], v[6:7], 0, s[38:39]
	global_load_dwordx4 v[76:79], v3, s[8:9]
	global_load_dwordx4 v[80:83], v3, s[8:9] offset:256
	global_load_dwordx4 v[68:71], v3, s[8:9] offset:512
	global_load_dwordx4 v[72:75], v3, s[8:9] offset:768
	s_cmp_gt_u32 s10, 1
	global_load_lds_dwordx4 v[6:7], off
	v_lshlrev_b32_e32 v6, 4, v10
	v_mov_b32_e32 v7, v3
	s_mov_b32 s51, 0
	s_cselect_b32 s50, 0x88000, 0
	v_lshl_add_u64 v[8:9], v[170:171], 0, v[6:7]
	v_lshl_add_u64 v[4:5], v[170:171], 0, s[50:51]
	v_lshl_add_u64 v[8:9], v[8:9], 0, s[44:45]
	s_mov_b32 m0, s59
	v_lshlrev_b32_e32 v22, 3, v10
	global_load_lds_dwordx4 v[8:9], off
	v_lshl_add_u64 v[8:9], v[4:5], 0, v[2:3]
	v_lshl_add_u64 v[8:9], v[8:9], 0, s[38:39]
	s_mov_b32 m0, s60
	v_lshl_add_u64 v[4:5], v[4:5], 0, v[6:7]
	global_load_lds_dwordx4 v[8:9], off
	v_lshl_add_u64 v[4:5], v[4:5], 0, s[44:45]
	s_mov_b32 m0, s61
	v_lshlrev_b32_e32 v2, 7, v211
	global_load_lds_dwordx4 v[4:5], off
	v_mad_i64_i32 v[4:5], s[4:5], v194, s58, 0
	v_or3_b32 v219, v2, v203, v204
	v_mad_u64_u32 v[4:5], s[4:5], s16, v1, v[4:5]
	v_bitop3_b32 v2, v206, 7, v213 bitop3:0x48
	v_lshl_or_b32 v8, v2, 4, v4
	v_mov_b32_e32 v9, v5
	v_or_b32_e32 v4, v4, v6
	v_mov_b32_e32 v18, v3
	v_mov_b32_e32 v19, v3
	v_lshl_add_u64 v[174:175], s[26:27], 0, v[8:9]
	v_lshl_add_u64 v[176:177], s[28:29], 0, v[4:5]
	s_add_u32 s52, s56, s6
	v_mov_b32_e32 v187, v186
	v_mov_b32_e32 v4, v3
	v_mov_b32_e32 v5, v3
	v_mov_b32_e32 v6, v3
	v_mov_b32_e32 v8, v3
	v_mov_b32_e32 v9, v3
	v_mov_b32_e32 v10, v3
	v_mov_b32_e32 v11, v3
	v_mov_b32_e32 v12, v3
	v_mov_b32_e32 v13, v3
	v_mov_b32_e32 v14, v3
	v_mov_b32_e32 v15, v3
	v_mov_b32_e32 v16, v3
	v_mov_b32_e32 v17, v3
	v_lshlrev_b32_e32 v2, 1, v20
	v_lshlrev_b32_e32 v178, 1, v22
	v_mov_b64_e32 v[50:51], v[18:19]
	v_mov_b64_e32 v[34:35], v[18:19]
	v_mov_b64_e32 v[66:67], v[18:19]
	v_cmp_gt_u32_e64 s[10:11], 32, v214
	v_lshlrev_b32_e32 v165, 4, v207
	v_lshlrev_b32_e32 v216, 4, v208
	v_lshlrev_b32_e32 v217, 4, v209
	v_lshlrev_b32_e32 v218, 4, v212
	v_sub_u32_e32 v220, 0, v202
	s_addc_u32 s53, s57, s7
	v_mov_b32_e32 v172, v3
	v_mov_b32_e32 v173, v3
	s_mov_b32 s16, 0x8000
	s_mov_b32 s50, s51
	v_mov_b64_e32 v[48:49], v[16:17]
	v_mov_b64_e32 v[46:47], v[14:15]
	v_mov_b64_e32 v[44:45], v[12:13]
	v_mov_b64_e32 v[42:43], v[10:11]
	v_mov_b64_e32 v[40:41], v[8:9]
	v_mov_b64_e32 v[38:39], v[6:7]
	v_mov_b64_e32 v[36:37], v[4:5]
	s_waitcnt vmcnt(0)
	v_mov_b64_e32 v[162:163], v[78:79]
	v_mov_b64_e32 v[158:159], v[82:83]
	v_mov_b64_e32 v[154:155], v[70:71]
	v_mov_b64_e32 v[150:151], v[74:75]
	v_mov_b64_e32 v[32:33], v[16:17]
	v_mov_b64_e32 v[30:31], v[14:15]
	v_mov_b64_e32 v[28:29], v[12:13]
	v_mov_b64_e32 v[26:27], v[10:11]
	v_mov_b64_e32 v[24:25], v[8:9]
	v_mov_b64_e32 v[22:23], v[6:7]
	v_mov_b64_e32 v[20:21], v[4:5]
	v_mov_b64_e32 v[64:65], v[16:17]
	v_mov_b64_e32 v[62:63], v[14:15]
	v_mov_b64_e32 v[60:61], v[12:13]
	v_mov_b64_e32 v[58:59], v[10:11]
	v_mov_b64_e32 v[56:57], v[8:9]
	v_mov_b64_e32 v[54:55], v[6:7]
	v_mov_b64_e32 v[52:53], v[4:5]
	v_mov_b64_e32 v[180:181], v[186:187]
	v_mov_b64_e32 v[148:149], v[72:73]
	v_mov_b64_e32 v[152:153], v[68:69]
	v_mov_b64_e32 v[156:157], v[80:81]
	v_mov_b64_e32 v[160:161], v[76:77]
	v_mov_b32_e32 v86, v214
	v_mov_b32_e32 v90, 0
	v_cmp_gt_u32_e32 vcc, 32, v86
	v_mov_b32_e32 v84, 0
	v_mov_b32_e32 v85, 0
	s_and_saveexec_b64 s[4:5], vcc
	s_cbranch_execz .Ldsa_ef_done
	v_lshrrev_b32_e32 v85, 3, v86
	v_cmp_gt_u32_e32 vcc, 8, v86
	s_nop 1
	v_cndmask_b32_e32 v84, 0, v200, vcc
	v_cmp_eq_u32_e32 vcc, 1, v85
	s_nop 1
	v_cndmask_b32_e64 v86, 0, 1.0, vcc
	v_cmp_eq_u32_e32 vcc, 2, v85
	v_or_b32_e32 v84, v86, v84
	s_nop 0
	v_cndmask_b32_e32 v86, 0, v200, vcc
	v_cmp_eq_u32_e32 vcc, 3, v85
	s_nop 1
	v_cndmask_b32_e64 v85, 0, 1.0, vcc
	v_or_b32_e32 v85, v86, v85
.Ldsa_ef_done:
	s_or_b64 exec, exec, s[4:5]
	v_mov_b32_e32 v254, v84
	v_mov_b32_e32 v255, v85
	v_mov_b32_e32 v252, 0xc700c700
	s_mov_b32 s98, 0xffff3900

.LBB0_720:
	v_mov_b32_e32 v90, 0
	v_mov_b32_e32 v84, v254
	v_mov_b32_e32 v85, v255
.LBB0_722:
	v_mov_b32_e32 v92, v90
	v_mov_b32_e32 v93, v90
	v_mov_b32_e32 v88, v90
	v_mov_b32_e32 v89, v90
	s_and_saveexec_b64 s[4:5], s[10:11]
	s_cbranch_execz .LBB0_724
	v_bfe_u32 v68, v68, v215, 1
	v_bfe_u32 v72, v72, v215, 1
	v_lshl_or_b32 v68, v72, 16, v68
	v_mad_i32_i24 v93, v68, s98, v252
	v_bfe_u32 v68, v77, v215, 1
	v_bfe_u32 v72, v81, v215, 1
	v_lshl_or_b32 v68, v72, 16, v68
	v_mad_i32_i24 v88, v68, s98, v252
	v_bfe_u32 v76, v76, v215, 1
	v_bfe_u32 v80, v80, v215, 1
	v_lshl_or_b32 v76, v80, 16, v76
	v_mad_i32_i24 v92, v76, s98, v252
	v_bfe_u32 v68, v69, v215, 1
	v_bfe_u32 v69, v73, v215, 1
	v_lshl_or_b32 v68, v69, 16, v68
	v_mad_i32_i24 v89, v68, s98, v252
.LBB0_724:
	s_or_b64 exec, exec, s[4:5]
	v_mov_b32_e32 v98, 0
	v_mov_b32_e32 v116, 0
	v_mov_b32_e32 v117, 0
	v_mov_b32_e32 v96, 0
	v_mov_b32_e32 v97, 0
	s_and_saveexec_b64 s[4:5], s[10:11]
	s_cbranch_execz .LBB0_726
	v_bfe_u32 v68, v78, v215, 1
	v_bfe_u32 v69, v82, v215, 1
	v_lshl_or_b32 v68, v69, 16, v68
	v_mad_i32_i24 v116, v68, s98, v252
	v_bfe_u32 v68, v70, v215, 1
	v_bfe_u32 v69, v74, v215, 1
	v_lshl_or_b32 v68, v69, 16, v68
	v_mad_i32_i24 v117, v68, s98, v252
	v_bfe_u32 v68, v79, v215, 1
	v_bfe_u32 v69, v83, v215, 1
	v_lshl_or_b32 v68, v69, 16, v68
	v_mad_i32_i24 v96, v68, s98, v252
	v_bfe_u32 v68, v71, v215, 1
	v_bfe_u32 v69, v75, v215, 1
	v_lshl_or_b32 v68, v69, 16, v68
	v_mad_i32_i24 v97, v68, s98, v252
